# two-group GEMM start stagger with 2 sleeps per phase instead of 3
# baseline (speedup 1.0000x reference)
; #define LAS __attribute__((address_space(3)))
; __device__ __forceinline__ unsigned xb_add(unsigned* p, unsigned v) { return __hip_atomic_fetch_add(p, v, __ATOMIC_RELAXED, __HIP_MEMORY_SCOPE_AGENT); }
; __device__ __forceinline__ unsigned xb_xcc_id() { return (unsigned)__builtin_amdgcn_s_getreg((3 << 11) | 20) & 0xFu; }
; __device__ __forceinline__ XcdBarrier xcd_barrier_post(unsigned* bar, volatile LAS unsigned* st) {
;     XcdBarrier b; b.bar = bar; b.x = xb_xcc_id(); b.st = st;
;     if (threadIdx.x == 0) (void)xb_add(&bar[XB_XCNT(b.x)], 1u);
;     return b;
; }
; __global__ void __launch_bounds__(NWAVES * 64, 2) hymba_fwd(Args A) {
;     ...
;     grid.sync();
;     XcdBarrier bar = xcd_barrier_post((unsigned*)ws, bst);
;     {
;         pg8::Gemm g{(const pg8::bf16_t*)(ws + WS_XA), (const pg8::bf16_t*)(ws + WS_W1), M1, DIN, DM, DM};
.LBB0_102:
	s_or_b64 exec, exec, s[0:1]
	s_barrier
	s_cmp_lt_u32 s22, 36
	s_cbranch_scc1 .Lstag_p1
	s_bitcmp1_b32 s22, 3
	s_cbranch_scc0 .Lstag_p1
	s_sleep 127
	s_sleep 127
.Lstag_p1:
	s_getreg_b32 s0, hwreg(HW_REG_XCC_ID, 0, 4)
	s_and_b32 s33, s0, 15
	s_and_saveexec_b64 s[0:1], s[30:31]
	s_cbranch_execz .LBB0_105
	s_mov_b64 s[2:3], exec
	v_mbcnt_lo_u32_b32 v0, s2, 0
	v_mbcnt_hi_u32_b32 v0, s3, v0
	v_cmp_eq_u32_e32 vcc, 0, v0
	s_and_b64 s[4:5], exec, vcc
	s_mov_b64 exec, s[4:5]
	s_cbranch_execz .LBB0_105
	s_lshl_b32 s4, s33, 8
	s_bcnt1_i32_b64 s2, s[2:3]
	v_mov_b32_e32 v0, s4
	v_mov_b32_e32 v1, s2
	global_atomic_add v0, v1, s[80:81] offset:1024

;     __host__ __device__ bool next(int i, Unit& u) const { return at((long)i * G + c, u); }
;     __device__ bool next(int i, Unit& u) const { const long L = (long)i * G + c; if (L >= 128) return false; u.pm = 64 + (int)(L >> 6); u.pn = (int)(L >> 4) & 3; u.kofs = ((int)L & 15) * 256; return true; }
; #define PG8_BAR __builtin_amdgcn_s_barrier()
; template <class Epi, class Sched, bool ALIGN_EPI = false, bool SP2 = false>
; __device__ __forceinline__ void gemm_phase(PG8_LAS unsigned char* lds, const Gemm g, const Sched& S, const Epi& E) {
;     ...
;     for (int i = 0; i < 2; ++i) { int R, C; stage_rc(tid * 16 + i * 8192, R, C); const int Rb = Epi::PERM ? ((R & ~31) + perm32(R & 31)) : R;
;         voffA[i] = (unsigned)(R * K + C) * 2u; voffB[i] = (unsigned)(Rb * K + C) * 2u; }
;     const size_t kstep = (size_t)(BK * 2);
;     const size_t hstep = (size_t)HALF * K * 2;
;     const size_t tstep = 2 * hstep;
;     const unsigned ldsw = (unsigned)wid * 1024u;
;     const int aoff = lds_byte(wr * 64 + fr, fq * 8), boff = lds_byte(wc * 32 + fr, fq * 8);
;     ...
;     Unit cur, nxt; int ui = 0;
;     if (!S.next(0, cur)) return;
;     f32x4 acc[2][2][4][2];
; #pragma unroll
;     for (int a = 0; a < 2; ++a)
; #pragma unroll
;         for (int b = 0; b < 2; ++b)
; #pragma unroll
;             for (int m = 0; m < 4; ++m)
; #pragma unroll
;                 for (int n = 0; n < 2; ++n) acc[a][b][m][n] = (f32x4){0.f, 0.f, 0.f, 0.f};
;     bf16x8 At[4][2], B0[2][2], B1[2][2];
;     const char* cA = (const char*)g.A + (size_t)cur.pm * tstep + (size_t)cur.kofs * 2; const char* cB = (const char*)g.Bt + (size_t)cur.pn * tstep + (size_t)cur.kofs * 2;
;     S.a_ready(cur);
;     if constexpr (SP2) {
;         PG8_STAGE(PG8_SB(0, 0), cB, voffB); PG8_STAGE(PG8_SB(0, 1), cB + hstep, voffB); PG8_STAGE(PG8_SA(0, 0), cA, voffA); PG8_STAGE(PG8_SA(0, 1), cA + hstep, voffA);
;         if (wr == 1) PG8_BAR;
; __global__ void __launch_bounds__(NWAVES * 64, 2) hymba_fwd(Args A) {
;     ...
;     xcd_barrier(bar);
;     {
;         pg8::Gemm g{(const pg8::bf16_t*)(ws + WS_X1B), (const pg8::bf16_t*)(ws + WS_W3), M2, DFF, DM, DM};
;         pg8::StaticOrder S; S.init(M2, DFF, G, bx);
;         pg8::Epi3 E{(const float*)(ws + WS_SS2), (pg8::bf16_t*)(ws + WS_H)};
;         pg8::gemm_phase<pg8::Epi3, pg8::StaticOrder, true, true>(lds, g, S, E);
.LBB0_746:
	s_or_b64 exec, exec, s[0:1]
	v_mov_b32_e32 v9, v138
	s_waitcnt lgkmcnt(0)
	s_barrier
	s_cmp_lt_u32 s22, 32
	s_cbranch_scc1 .Lstag_p4
	s_bitcmp1_b32 s22, 3
	s_cbranch_scc0 .Lstag_p4
	s_sleep 127
	s_sleep 127
.Lstag_p4:
	s_cmpk_gt_i32 s22, 0x41f
	v_readfirstlane_b32 s5, v9
	s_cbranch_scc1 .LBB0_762
	v_lshlrev_b32_e32 v0, 4, v9
	v_add_u32_e32 v1, 0x2000, v0
	v_ashrrev_i32_e32 v2, 31, v1
	v_lshrrev_b32_e32 v2, 22, v2
	v_add_u32_e32 v2, v1, v2
	v_ashrrev_i32_e32 v8, 10, v2
	v_mul_i32_i24_e32 v2, 0x400, v8
	v_sub_u32_e32 v1, v1, v2
	v_lshrrev_b32_e32 v2, 4, v1
	v_bitop3_b32 v1, v2, v1, 32 bitop3:0x6c
	v_ashrrev_i32_e32 v2, 31, v1
	v_lshrrev_b32_e32 v2, 26, v2
	v_add_u32_e32 v2, v1, v2
	v_lshlrev_b32_e32 v3, 3, v8
	v_ashrrev_i32_e32 v10, 6, v2
	v_and_b32_e32 v3, -16, v3
	v_add_u32_e32 v3, v10, v3
	v_and_b32_e32 v4, 3, v10
	s_mov_b32 s0, 0x1fffe0
	v_lshrrev_b32_e32 v5, 2, v3
	v_lshlrev_b32_e32 v6, 1, v3
	v_and_b32_e32 v2, 0xc0, v2
	v_and_or_b32 v4, v3, s0, v4
	v_and_b32_e32 v5, 4, v5
	v_and_b32_e32 v6, 24, v6
	v_sub_u32_e32 v1, v1, v2
	v_mov_b32_e32 v2, 1
	v_or3_b32 v4, v4, v5, v6
	v_lshlrev_b32_e32 v5, 5, v8
	v_ashrrev_i16_sdwa v1, v2, sext(v1) dst_sel:DWORD dst_unused:UNUSED_PAD src0_sel:DWORD src1_sel:BYTE_0
	v_and_b32_e32 v5, 32, v5
	v_bfe_i32 v11, v1, 0, 16
	v_add_lshl_u32 v1, v5, v11, 1
	v_lshl_add_u32 v128, v4, 11, v1
	v_lshl_add_u32 v130, v3, 11, v1
	v_bfe_i32 v1, v9, 27, 1
	v_lshrrev_b32_e32 v1, 22, v1
	v_add_u32_e32 v1, v0, v1
	v_and_b32_e32 v1, 0xfffffc00, v1
	v_sub_u32_e32 v0, v0, v1
	v_lshrrev_b32_e32 v1, 4, v0
	v_ashrrev_i32_e32 v3, 31, v9
	v_bitop3_b32 v0, v1, v0, 32 bitop3:0x6c
	v_lshrrev_b32_e32 v3, 26, v3
	v_ashrrev_i32_e32 v1, 31, v0
	v_add_u32_e32 v3, v9, v3
	v_lshrrev_b32_e32 v1, 26, v1
	v_ashrrev_i32_e32 v13, 6, v3
	v_add_u32_e32 v1, v0, v1
	v_lshlrev_b32_e32 v3, 3, v13
	v_ashrrev_i32_e32 v12, 6, v1
	v_and_b32_e32 v3, -16, v3
	s_add_u32 s23, s80, 0x900000
	v_add_u32_e32 v3, v12, v3
	v_and_b32_e32 v4, 3, v12
	s_addc_u32 s33, s81, 0
	v_and_or_b32 v4, v3, s0, v4
	s_ashr_i32 s0, s22, 31
	s_lshr_b32 s0, s0, 29
	s_add_i32 s0, s22, s0
	s_ashr_i32 s14, s5, 6
	s_ashr_i32 s1, s0, 3
	s_and_b32 s0, s0, -8
	s_ashr_i32 s6, s5, 8
	s_lshl_b32 s38, s14, 10
	s_sub_i32 s0, s22, s0
	s_cmp_lt_i32 s0, 0
	s_movk_i32 s39, 0x85
	s_cselect_b32 s4, s39, 0x84
	s_mul_i32 s0, s0, s4
	s_add_i32 s0, s0, s1
	s_ashr_i32 s1, s0, 31
	s_lshr_b32 s1, s1, 25
	s_add_i32 s1, s0, s1
	v_lshrrev_b32_e32 v5, 2, v3
	v_lshlrev_b32_e32 v6, 1, v3
	v_and_b32_e32 v1, 0xc0, v1
	s_ashr_i32 s1, s1, 7
	v_and_b32_e32 v5, 4, v5
	v_and_b32_e32 v6, 24, v6
	v_sub_u32_e32 v0, v0, v1
	s_lshl_b32 s7, s1, 3
	v_or3_b32 v4, v4, v5, v6
	v_lshlrev_b32_e32 v5, 5, v13
	v_ashrrev_i16_sdwa v0, v2, sext(v0) dst_sel:DWORD dst_unused:UNUSED_PAD src0_sel:DWORD src1_sel:BYTE_0
	s_sub_i32 s4, 0x42, s7
	s_lshl_b32 s1, s1, 7
	v_and_b32_e32 v5, 32, v5
	v_bfe_i32 v14, v0, 0, 16
	s_min_u32 s12, s4, 8
	s_sub_i32 s13, s0, s1
	v_add_lshl_u32 v0, v5, v14, 1
	s_sext_i32_i8 s0, s13
	v_cvt_f32_ubyte0_e32 v2, s12
	v_lshl_add_u32 v132, v4, 11, v0
	v_cvt_f32_i32_e32 v1, s0
	v_rcp_iflag_f32_e32 v4, v2
	v_lshl_add_u32 v134, v3, 11, v0
	s_ashr_i32 s0, s0, 30
	s_or_b32 s4, s0, 1
	v_mul_f32_e32 v0, v1, v4
	v_trunc_f32_e32 v0, v0
	v_fma_f32 v1, -v0, v2, v1
	v_cvt_i32_f32_e32 v0, v0
	v_cmp_ge_f32_e64 s[0:1], |v1|, v2
	s_and_b64 s[0:1], s[0:1], exec
	s_cselect_b32 s0, s4, 0
	v_readfirstlane_b32 s1, v0
	s_add_i32 s4, s1, s0
	s_mul_i32 s0, s4, s12
	s_sub_i32 s0, s13, s0
	s_sext_i32_i8 s0, s0
	s_add_i32 s0, s7, s0
	s_ashr_i32 s1, s0, 31
	s_bfe_i64 s[16:17], s[4:5], 0x80000
	s_lshl_b64 s[12:13], s[0:1], 19
	s_lshl_b64 s[16:17], s[16:17], 19
	s_add_u32 s34, s23, s16
	s_addc_u32 s35, s33, s17
	s_add_i32 s40, s38, 0
	s_add_i32 m0, s40, 0x10000
	v_mov_b32_e32 v141, 0
	global_load_lds_dwordx4 v132, s[34:35]
	s_add_i32 m0, s40, 0x12000
	s_add_u32 s16, s34, 0x40000
	global_load_lds_dwordx4 v128, s[34:35]
	s_addc_u32 s17, s35, 0
	s_add_i32 m0, s40, 0x14000
	v_mov_b32_e32 v133, v141
	global_load_lds_dwordx4 v132, s[16:17]
	s_add_i32 m0, s40, 0x16000
	s_add_u32 s30, s8, s12
	s_addc_u32 s31, s9, s13
	s_add_i32 s41, s40, 0x2000
	global_load_lds_dwordx4 v128, s[16:17]
	s_mov_b32 m0, s40
	s_add_u32 s12, s30, 0x40000
	global_load_lds_dwordx4 v134, s[30:31]
	s_mov_b32 m0, s41
	s_addc_u32 s13, s31, 0
	s_add_i32 s42, s40, 0x4000
	global_load_lds_dwordx4 v130, s[30:31]
	s_mov_b32 m0, s42
	s_add_i32 s43, s40, 0x6000
	global_load_lds_dwordx4 v134, s[12:13]
	s_mov_b32 m0, s43
	v_mov_b32_e32 v129, v141
	global_load_lds_dwordx4 v130, s[12:13]
	v_mov_b32_e32 v135, v141
	v_mov_b32_e32 v131, v141
	s_cmp_eq_u32 s6, 1
	s_mov_b32 s7, 0
	v_lshl_add_u64 v[6:7], s[34:35], 0, v[132:133]
	v_lshl_add_u64 v[4:5], s[34:35], 0, v[128:129]
	v_lshl_add_u64 v[0:1], s[30:31], 0, v[134:135]
	s_cselect_b64 s[12:13], -1, 0
	s_cmp_lg_u32 s6, 1
	v_lshl_add_u64 v[2:3], s[30:31], 0, v[130:131]
	s_cbranch_scc1 .LBB0_749
	s_barrier
